# P6 compression MLP K loop: W1 and token rows copied through LDS in 8 chunks with coalesced loads (3 chunks in flight) instead of per-wave strided half-line gathers; same MFMA order
# speedup vs baseline: 1.0230x; 1.0147x over previous
.LBB0_358:
	s_and_b32 s2, s25, 15
	v_lshl_or_b32 v33, s2, 8, v32
	s_ashr_i32 s2, s16, 7
	s_ashr_i32 s3, s2, 31
	s_lshl_b64 s[8:9], s[2:3], 22
	s_add_u32 s8, s10, s8
	s_addc_u32 s9, s11, s9
	s_bfe_u32 s17, s16, 0x30004
	s_lshl_b32 s18, s17, 19
	s_add_u32 s8, s8, s18
	s_addc_u32 s9, s9, 0
	s_lshl_b64 s[18:19], s[2:3], 19
	v_mov_b32_e32 v0, 0
	v_lshl_add_u64 v[22:23], v[4:5], 1, s[8:9]
	v_lshl_add_u64 v[24:25], v[20:21], 0, s[18:19]
	v_mov_b32_e32 v1, v0
	v_mov_b32_e32 v2, v0
	v_mov_b32_e32 v3, v0
	s_add_u32 s100, s14, s18
	s_addc_u32 s101, s15, s19
	s_sub_u32 s100, s100, 0x200000
	s_subb_u32 s101, s101, 0
	v_mbcnt_lo_u32_b32 v46, -1, 0
	v_mbcnt_hi_u32_b32 v46, -1, v46
	s_lshl_b32 s18, s26, 6
	v_and_b32_e32 v44, 15, v46
	v_lshrrev_b32_e32 v45, 4, v46
	v_add_u32_e32 v46, s18, v46
	v_and_b32_e32 v47, 31, v46
	v_lshrrev_b32_e32 v48, 5, v46
	v_lshlrev_b32_e32 v49, 12, v48
	v_lshl_add_u32 v50, v47, 4, v49
	v_add_u32_e32 v51, 0x10000, v50
	v_add_u32_e32 v52, 0x20000, v50
	v_add_u32_e32 v53, 0x30000, v50
	v_add_u32_e32 v54, 0x40000, v50
	v_add_u32_e32 v55, 0x50000, v50
	v_add_u32_e32 v56, 0x60000, v50
	v_add_u32_e32 v57, 0x70000, v50
	s_and_b32 s19, s25, 15
	s_lshl_b32 s19, s19, 8
	v_lshrrev_b32_e32 v58, 3, v47
	v_lshl_add_u32 v58, v48, 4, v58
	v_add_u32_e32 v58, s19, v58
	v_and_b32_e32 v59, 7, v47
	v_lshlrev_b32_e32 v59, 4, v59
	v_mul_u32_u24_e32 v60, 0x220, v48
	v_lshl_add_u32 v60, v47, 4, v60
	v_add_u32_e32 v61, 0x11000, v60
	s_lshl_b32 s18, s26, 4
	v_add_u32_e32 v62, s18, v44
	v_mul_u32_u24_e32 v62, 0x220, v62
	v_lshl_add_u32 v62, v45, 4, v62
	v_mul_u32_u24_e32 v63, 0x220, v44
	v_lshl_add_u32 v63, v45, 4, v63
	v_add_u32_e32 v63, 0x11000, v63
	global_load_dwordx4 v[64:67], v50, s[100:101]
	global_load_dwordx4 v[68:71], v51, s[100:101]
	global_load_dwordx4 v[72:75], v52, s[100:101]
	global_load_dwordx4 v[76:79], v53, s[100:101]
	global_load_dwordx4 v[80:83], v54, s[100:101]
	global_load_dwordx4 v[84:87], v55, s[100:101]
	global_load_dwordx4 v[88:91], v56, s[100:101]
	global_load_dwordx4 v[92:95], v57, s[100:101]
	v_min_u32_e32 v43, 0xfff, v58
	v_lshl_add_u32 v43, v43, 7, v59
	global_load_dwordx4 v[96:99], v43, s[8:9]
	global_load_dwordx4 v[100:103], v50, s[100:101] offset:512
	global_load_dwordx4 v[104:107], v51, s[100:101] offset:512
	global_load_dwordx4 v[108:111], v52, s[100:101] offset:512
	global_load_dwordx4 v[112:115], v53, s[100:101] offset:512
	global_load_dwordx4 v[116:119], v54, s[100:101] offset:512
	global_load_dwordx4 v[120:123], v55, s[100:101] offset:512
	global_load_dwordx4 v[124:127], v56, s[100:101] offset:512
	global_load_dwordx4 v[128:131], v57, s[100:101] offset:512
	v_add_u32_e32 v43, 4, v58
	v_min_u32_e32 v43, 0xfff, v43
	v_lshl_add_u32 v43, v43, 7, v59
	global_load_dwordx4 v[132:135], v43, s[8:9]
	global_load_dwordx4 v[140:143], v50, s[100:101] offset:1024
	global_load_dwordx4 v[144:147], v51, s[100:101] offset:1024
	global_load_dwordx4 v[148:151], v52, s[100:101] offset:1024
	global_load_dwordx4 v[152:155], v53, s[100:101] offset:1024
	global_load_dwordx4 v[156:159], v54, s[100:101] offset:1024
	global_load_dwordx4 v[160:163], v55, s[100:101] offset:1024
	global_load_dwordx4 v[164:167], v56, s[100:101] offset:1024
	global_load_dwordx4 v[168:171], v57, s[100:101] offset:1024
	v_add_u32_e32 v43, 8, v58
	v_min_u32_e32 v43, 0xfff, v43
	v_lshl_add_u32 v43, v43, 7, v59
	global_load_dwordx4 v[172:175], v43, s[8:9]
	s_barrier
	s_waitcnt vmcnt(18)
	ds_write_b128 v60, v[64:67]
	ds_write_b128 v60, v[68:71] offset:8704
	ds_write_b128 v60, v[72:75] offset:17408
	ds_write_b128 v60, v[76:79] offset:26112
	ds_write_b128 v60, v[80:83] offset:34816
	ds_write_b128 v60, v[84:87] offset:43520
	ds_write_b128 v60, v[88:91] offset:52224
	ds_write_b128 v60, v[92:95] offset:60928
	ds_write_b128 v61, v[96:99]
	s_waitcnt lgkmcnt(0)
	global_load_dwordx4 v[64:67], v50, s[100:101] offset:1536
	global_load_dwordx4 v[68:71], v51, s[100:101] offset:1536
	global_load_dwordx4 v[72:75], v52, s[100:101] offset:1536
	global_load_dwordx4 v[76:79], v53, s[100:101] offset:1536
	global_load_dwordx4 v[80:83], v54, s[100:101] offset:1536
	global_load_dwordx4 v[84:87], v55, s[100:101] offset:1536
	global_load_dwordx4 v[88:91], v56, s[100:101] offset:1536
	global_load_dwordx4 v[92:95], v57, s[100:101] offset:1536
	v_add_u32_e32 v43, 12, v58
	v_min_u32_e32 v43, 0xfff, v43
	v_lshl_add_u32 v43, v43, 7, v59
	global_load_dwordx4 v[96:99], v43, s[8:9]
	s_barrier
	ds_read_b128 v[176:179], v62
	ds_read_b128 v[180:183], v63
	ds_read_b128 v[184:187], v62 offset:64
	ds_read_b128 v[188:191], v63 offset:64
	ds_read_b128 v[192:195], v62 offset:128
	ds_read_b128 v[196:199], v63 offset:128
	ds_read_b128 v[200:203], v62 offset:192
	ds_read_b128 v[204:207], v63 offset:192
	s_waitcnt lgkmcnt(0)
	v_mfma_f32_16x16x32_bf16 v[0:3], v[176:179], v[180:183], v[0:3]
	v_mfma_f32_16x16x32_bf16 v[0:3], v[184:187], v[188:191], v[0:3]
	v_mfma_f32_16x16x32_bf16 v[0:3], v[192:195], v[196:199], v[0:3]
	v_mfma_f32_16x16x32_bf16 v[0:3], v[200:203], v[204:207], v[0:3]
	ds_read_b128 v[176:179], v62 offset:256
	ds_read_b128 v[180:183], v63 offset:256
	ds_read_b128 v[184:187], v62 offset:320
	ds_read_b128 v[188:191], v63 offset:320
	ds_read_b128 v[192:195], v62 offset:384
	ds_read_b128 v[196:199], v63 offset:384
	ds_read_b128 v[200:203], v62 offset:448
	ds_read_b128 v[204:207], v63 offset:448
	s_waitcnt lgkmcnt(0)
	v_mfma_f32_16x16x32_bf16 v[0:3], v[176:179], v[180:183], v[0:3]
	v_mfma_f32_16x16x32_bf16 v[0:3], v[184:187], v[188:191], v[0:3]
	v_mfma_f32_16x16x32_bf16 v[0:3], v[192:195], v[196:199], v[0:3]
	v_mfma_f32_16x16x32_bf16 v[0:3], v[200:203], v[204:207], v[0:3]
	s_barrier
	s_waitcnt vmcnt(18)
	ds_write_b128 v60, v[100:103]
	ds_write_b128 v60, v[104:107] offset:8704
	ds_write_b128 v60, v[108:111] offset:17408
	ds_write_b128 v60, v[112:115] offset:26112
	ds_write_b128 v60, v[116:119] offset:34816
	ds_write_b128 v60, v[120:123] offset:43520
	ds_write_b128 v60, v[124:127] offset:52224
	ds_write_b128 v60, v[128:131] offset:60928
	ds_write_b128 v61, v[132:135]
	s_waitcnt lgkmcnt(0)
	global_load_dwordx4 v[100:103], v50, s[100:101] offset:2048
	global_load_dwordx4 v[104:107], v51, s[100:101] offset:2048
	global_load_dwordx4 v[108:111], v52, s[100:101] offset:2048
	global_load_dwordx4 v[112:115], v53, s[100:101] offset:2048
	global_load_dwordx4 v[116:119], v54, s[100:101] offset:2048
	global_load_dwordx4 v[120:123], v55, s[100:101] offset:2048
	global_load_dwordx4 v[124:127], v56, s[100:101] offset:2048
	global_load_dwordx4 v[128:131], v57, s[100:101] offset:2048
	v_add_u32_e32 v43, 16, v58
	v_min_u32_e32 v43, 0xfff, v43
	v_lshl_add_u32 v43, v43, 7, v59
	global_load_dwordx4 v[132:135], v43, s[8:9]
	s_barrier
	ds_read_b128 v[176:179], v62
	ds_read_b128 v[180:183], v63
	ds_read_b128 v[184:187], v62 offset:64
	ds_read_b128 v[188:191], v63 offset:64
	ds_read_b128 v[192:195], v62 offset:128
	ds_read_b128 v[196:199], v63 offset:128
	ds_read_b128 v[200:203], v62 offset:192
	ds_read_b128 v[204:207], v63 offset:192
	s_waitcnt lgkmcnt(0)
	v_mfma_f32_16x16x32_bf16 v[0:3], v[176:179], v[180:183], v[0:3]
	v_mfma_f32_16x16x32_bf16 v[0:3], v[184:187], v[188:191], v[0:3]
	v_mfma_f32_16x16x32_bf16 v[0:3], v[192:195], v[196:199], v[0:3]
	v_mfma_f32_16x16x32_bf16 v[0:3], v[200:203], v[204:207], v[0:3]
	ds_read_b128 v[176:179], v62 offset:256
	ds_read_b128 v[180:183], v63 offset:256
	ds_read_b128 v[184:187], v62 offset:320
	ds_read_b128 v[188:191], v63 offset:320
	ds_read_b128 v[192:195], v62 offset:384
	ds_read_b128 v[196:199], v63 offset:384
	ds_read_b128 v[200:203], v62 offset:448
	ds_read_b128 v[204:207], v63 offset:448
	s_waitcnt lgkmcnt(0)
	v_mfma_f32_16x16x32_bf16 v[0:3], v[176:179], v[180:183], v[0:3]
	v_mfma_f32_16x16x32_bf16 v[0:3], v[184:187], v[188:191], v[0:3]
	v_mfma_f32_16x16x32_bf16 v[0:3], v[192:195], v[196:199], v[0:3]
	v_mfma_f32_16x16x32_bf16 v[0:3], v[200:203], v[204:207], v[0:3]
	s_barrier
	s_waitcnt vmcnt(18)
	ds_write_b128 v60, v[140:143]
	ds_write_b128 v60, v[144:147] offset:8704
	ds_write_b128 v60, v[148:151] offset:17408
	ds_write_b128 v60, v[152:155] offset:26112
	ds_write_b128 v60, v[156:159] offset:34816
	ds_write_b128 v60, v[160:163] offset:43520
	ds_write_b128 v60, v[164:167] offset:52224
	ds_write_b128 v60, v[168:171] offset:60928
	ds_write_b128 v61, v[172:175]
	s_waitcnt lgkmcnt(0)
	global_load_dwordx4 v[140:143], v50, s[100:101] offset:2560
	global_load_dwordx4 v[144:147], v51, s[100:101] offset:2560
	global_load_dwordx4 v[148:151], v52, s[100:101] offset:2560
	global_load_dwordx4 v[152:155], v53, s[100:101] offset:2560
	global_load_dwordx4 v[156:159], v54, s[100:101] offset:2560
	global_load_dwordx4 v[160:163], v55, s[100:101] offset:2560
	global_load_dwordx4 v[164:167], v56, s[100:101] offset:2560
	global_load_dwordx4 v[168:171], v57, s[100:101] offset:2560
	v_add_u32_e32 v43, 20, v58
	v_min_u32_e32 v43, 0xfff, v43
	v_lshl_add_u32 v43, v43, 7, v59
	global_load_dwordx4 v[172:175], v43, s[8:9]
	s_barrier
	ds_read_b128 v[176:179], v62
	ds_read_b128 v[180:183], v63
	ds_read_b128 v[184:187], v62 offset:64
	ds_read_b128 v[188:191], v63 offset:64
	ds_read_b128 v[192:195], v62 offset:128
	ds_read_b128 v[196:199], v63 offset:128
	ds_read_b128 v[200:203], v62 offset:192
	ds_read_b128 v[204:207], v63 offset:192
	s_waitcnt lgkmcnt(0)
	v_mfma_f32_16x16x32_bf16 v[0:3], v[176:179], v[180:183], v[0:3]
	v_mfma_f32_16x16x32_bf16 v[0:3], v[184:187], v[188:191], v[0:3]
	v_mfma_f32_16x16x32_bf16 v[0:3], v[192:195], v[196:199], v[0:3]
	v_mfma_f32_16x16x32_bf16 v[0:3], v[200:203], v[204:207], v[0:3]
	ds_read_b128 v[176:179], v62 offset:256
	ds_read_b128 v[180:183], v63 offset:256
	ds_read_b128 v[184:187], v62 offset:320
	ds_read_b128 v[188:191], v63 offset:320
	ds_read_b128 v[192:195], v62 offset:384
	ds_read_b128 v[196:199], v63 offset:384
	ds_read_b128 v[200:203], v62 offset:448
	ds_read_b128 v[204:207], v63 offset:448
	s_waitcnt lgkmcnt(0)
	v_mfma_f32_16x16x32_bf16 v[0:3], v[176:179], v[180:183], v[0:3]
	v_mfma_f32_16x16x32_bf16 v[0:3], v[184:187], v[188:191], v[0:3]
	v_mfma_f32_16x16x32_bf16 v[0:3], v[192:195], v[196:199], v[0:3]
	v_mfma_f32_16x16x32_bf16 v[0:3], v[200:203], v[204:207], v[0:3]
	s_barrier
	s_waitcnt vmcnt(18)
	ds_write_b128 v60, v[64:67]
	ds_write_b128 v60, v[68:71] offset:8704
	ds_write_b128 v60, v[72:75] offset:17408
	ds_write_b128 v60, v[76:79] offset:26112
	ds_write_b128 v60, v[80:83] offset:34816
	ds_write_b128 v60, v[84:87] offset:43520
	ds_write_b128 v60, v[88:91] offset:52224
	ds_write_b128 v60, v[92:95] offset:60928
	ds_write_b128 v61, v[96:99]
	s_waitcnt lgkmcnt(0)
	global_load_dwordx4 v[64:67], v50, s[100:101] offset:3072
	global_load_dwordx4 v[68:71], v51, s[100:101] offset:3072
	global_load_dwordx4 v[72:75], v52, s[100:101] offset:3072
	global_load_dwordx4 v[76:79], v53, s[100:101] offset:3072
	global_load_dwordx4 v[80:83], v54, s[100:101] offset:3072
	global_load_dwordx4 v[84:87], v55, s[100:101] offset:3072
	global_load_dwordx4 v[88:91], v56, s[100:101] offset:3072
	global_load_dwordx4 v[92:95], v57, s[100:101] offset:3072
	v_add_u32_e32 v43, 24, v58
	v_min_u32_e32 v43, 0xfff, v43
	v_lshl_add_u32 v43, v43, 7, v59
	global_load_dwordx4 v[96:99], v43, s[8:9]
	s_barrier
	ds_read_b128 v[176:179], v62
	ds_read_b128 v[180:183], v63
	ds_read_b128 v[184:187], v62 offset:64
	ds_read_b128 v[188:191], v63 offset:64
	ds_read_b128 v[192:195], v62 offset:128
	ds_read_b128 v[196:199], v63 offset:128
	ds_read_b128 v[200:203], v62 offset:192
	ds_read_b128 v[204:207], v63 offset:192
	s_waitcnt lgkmcnt(0)
	v_mfma_f32_16x16x32_bf16 v[0:3], v[176:179], v[180:183], v[0:3]
	v_mfma_f32_16x16x32_bf16 v[0:3], v[184:187], v[188:191], v[0:3]
	v_mfma_f32_16x16x32_bf16 v[0:3], v[192:195], v[196:199], v[0:3]
	v_mfma_f32_16x16x32_bf16 v[0:3], v[200:203], v[204:207], v[0:3]
	ds_read_b128 v[176:179], v62 offset:256
	ds_read_b128 v[180:183], v63 offset:256
	ds_read_b128 v[184:187], v62 offset:320
	ds_read_b128 v[188:191], v63 offset:320
	ds_read_b128 v[192:195], v62 offset:384
	ds_read_b128 v[196:199], v63 offset:384
	ds_read_b128 v[200:203], v62 offset:448
	ds_read_b128 v[204:207], v63 offset:448
	s_waitcnt lgkmcnt(0)
	v_mfma_f32_16x16x32_bf16 v[0:3], v[176:179], v[180:183], v[0:3]
	v_mfma_f32_16x16x32_bf16 v[0:3], v[184:187], v[188:191], v[0:3]
	v_mfma_f32_16x16x32_bf16 v[0:3], v[192:195], v[196:199], v[0:3]
	v_mfma_f32_16x16x32_bf16 v[0:3], v[200:203], v[204:207], v[0:3]
	s_barrier
	s_waitcnt vmcnt(18)
	ds_write_b128 v60, v[100:103]
	ds_write_b128 v60, v[104:107] offset:8704
	ds_write_b128 v60, v[108:111] offset:17408
	ds_write_b128 v60, v[112:115] offset:26112
	ds_write_b128 v60, v[116:119] offset:34816
	ds_write_b128 v60, v[120:123] offset:43520
	ds_write_b128 v60, v[124:127] offset:52224
	ds_write_b128 v60, v[128:131] offset:60928
	ds_write_b128 v61, v[132:135]
	s_waitcnt lgkmcnt(0)
	global_load_dwordx4 v[100:103], v50, s[100:101] offset:3584
	global_load_dwordx4 v[104:107], v51, s[100:101] offset:3584
	global_load_dwordx4 v[108:111], v52, s[100:101] offset:3584
	global_load_dwordx4 v[112:115], v53, s[100:101] offset:3584
	global_load_dwordx4 v[116:119], v54, s[100:101] offset:3584
	global_load_dwordx4 v[120:123], v55, s[100:101] offset:3584
	global_load_dwordx4 v[124:127], v56, s[100:101] offset:3584
	global_load_dwordx4 v[128:131], v57, s[100:101] offset:3584
	v_add_u32_e32 v43, 28, v58
	v_min_u32_e32 v43, 0xfff, v43
	v_lshl_add_u32 v43, v43, 7, v59
	global_load_dwordx4 v[132:135], v43, s[8:9]
	s_barrier
	ds_read_b128 v[176:179], v62
	ds_read_b128 v[180:183], v63
	ds_read_b128 v[184:187], v62 offset:64
	ds_read_b128 v[188:191], v63 offset:64
	ds_read_b128 v[192:195], v62 offset:128
	ds_read_b128 v[196:199], v63 offset:128
	ds_read_b128 v[200:203], v62 offset:192
	ds_read_b128 v[204:207], v63 offset:192
	s_waitcnt lgkmcnt(0)
	v_mfma_f32_16x16x32_bf16 v[0:3], v[176:179], v[180:183], v[0:3]
	v_mfma_f32_16x16x32_bf16 v[0:3], v[184:187], v[188:191], v[0:3]
	v_mfma_f32_16x16x32_bf16 v[0:3], v[192:195], v[196:199], v[0:3]
	v_mfma_f32_16x16x32_bf16 v[0:3], v[200:203], v[204:207], v[0:3]
	ds_read_b128 v[176:179], v62 offset:256
	ds_read_b128 v[180:183], v63 offset:256
	ds_read_b128 v[184:187], v62 offset:320
	ds_read_b128 v[188:191], v63 offset:320
	ds_read_b128 v[192:195], v62 offset:384
	ds_read_b128 v[196:199], v63 offset:384
	ds_read_b128 v[200:203], v62 offset:448
	ds_read_b128 v[204:207], v63 offset:448
	s_waitcnt lgkmcnt(0)
	v_mfma_f32_16x16x32_bf16 v[0:3], v[176:179], v[180:183], v[0:3]
	v_mfma_f32_16x16x32_bf16 v[0:3], v[184:187], v[188:191], v[0:3]
	v_mfma_f32_16x16x32_bf16 v[0:3], v[192:195], v[196:199], v[0:3]
	v_mfma_f32_16x16x32_bf16 v[0:3], v[200:203], v[204:207], v[0:3]
	s_barrier
	s_waitcnt vmcnt(18)
	ds_write_b128 v60, v[140:143]
	ds_write_b128 v60, v[144:147] offset:8704
	ds_write_b128 v60, v[148:151] offset:17408
	ds_write_b128 v60, v[152:155] offset:26112
	ds_write_b128 v60, v[156:159] offset:34816
	ds_write_b128 v60, v[160:163] offset:43520
	ds_write_b128 v60, v[164:167] offset:52224
	ds_write_b128 v60, v[168:171] offset:60928
	ds_write_b128 v61, v[172:175]
	s_waitcnt lgkmcnt(0)
	s_barrier
	ds_read_b128 v[176:179], v62
	ds_read_b128 v[180:183], v63
	ds_read_b128 v[184:187], v62 offset:64
	ds_read_b128 v[188:191], v63 offset:64
	ds_read_b128 v[192:195], v62 offset:128
	ds_read_b128 v[196:199], v63 offset:128
	ds_read_b128 v[200:203], v62 offset:192
	ds_read_b128 v[204:207], v63 offset:192
	s_waitcnt lgkmcnt(0)
	v_mfma_f32_16x16x32_bf16 v[0:3], v[176:179], v[180:183], v[0:3]
	v_mfma_f32_16x16x32_bf16 v[0:3], v[184:187], v[188:191], v[0:3]
	v_mfma_f32_16x16x32_bf16 v[0:3], v[192:195], v[196:199], v[0:3]
	v_mfma_f32_16x16x32_bf16 v[0:3], v[200:203], v[204:207], v[0:3]
	ds_read_b128 v[176:179], v62 offset:256
	ds_read_b128 v[180:183], v63 offset:256
	ds_read_b128 v[184:187], v62 offset:320
	ds_read_b128 v[188:191], v63 offset:320
	ds_read_b128 v[192:195], v62 offset:384
	ds_read_b128 v[196:199], v63 offset:384
	ds_read_b128 v[200:203], v62 offset:448
	ds_read_b128 v[204:207], v63 offset:448
	s_waitcnt lgkmcnt(0)
	v_mfma_f32_16x16x32_bf16 v[0:3], v[176:179], v[180:183], v[0:3]
	v_mfma_f32_16x16x32_bf16 v[0:3], v[184:187], v[188:191], v[0:3]
	v_mfma_f32_16x16x32_bf16 v[0:3], v[192:195], v[196:199], v[0:3]
	v_mfma_f32_16x16x32_bf16 v[0:3], v[200:203], v[204:207], v[0:3]
	s_barrier
	s_waitcnt vmcnt(9)
	ds_write_b128 v60, v[64:67]
	ds_write_b128 v60, v[68:71] offset:8704
	ds_write_b128 v60, v[72:75] offset:17408
	ds_write_b128 v60, v[76:79] offset:26112
	ds_write_b128 v60, v[80:83] offset:34816
	ds_write_b128 v60, v[84:87] offset:43520
	ds_write_b128 v60, v[88:91] offset:52224
	ds_write_b128 v60, v[92:95] offset:60928
	ds_write_b128 v61, v[96:99]
	s_waitcnt lgkmcnt(0)
	s_barrier
	ds_read_b128 v[176:179], v62
	ds_read_b128 v[180:183], v63
	ds_read_b128 v[184:187], v62 offset:64
	ds_read_b128 v[188:191], v63 offset:64
	ds_read_b128 v[192:195], v62 offset:128
	ds_read_b128 v[196:199], v63 offset:128
	ds_read_b128 v[200:203], v62 offset:192
	ds_read_b128 v[204:207], v63 offset:192
	s_waitcnt lgkmcnt(0)
	v_mfma_f32_16x16x32_bf16 v[0:3], v[176:179], v[180:183], v[0:3]
	v_mfma_f32_16x16x32_bf16 v[0:3], v[184:187], v[188:191], v[0:3]
	v_mfma_f32_16x16x32_bf16 v[0:3], v[192:195], v[196:199], v[0:3]
	v_mfma_f32_16x16x32_bf16 v[0:3], v[200:203], v[204:207], v[0:3]
	ds_read_b128 v[176:179], v62 offset:256
	ds_read_b128 v[180:183], v63 offset:256
	ds_read_b128 v[184:187], v62 offset:320
	ds_read_b128 v[188:191], v63 offset:320
	ds_read_b128 v[192:195], v62 offset:384
	ds_read_b128 v[196:199], v63 offset:384
	ds_read_b128 v[200:203], v62 offset:448
	ds_read_b128 v[204:207], v63 offset:448
	s_waitcnt lgkmcnt(0)
	v_mfma_f32_16x16x32_bf16 v[0:3], v[176:179], v[180:183], v[0:3]
	v_mfma_f32_16x16x32_bf16 v[0:3], v[184:187], v[188:191], v[0:3]
	v_mfma_f32_16x16x32_bf16 v[0:3], v[192:195], v[196:199], v[0:3]
	v_mfma_f32_16x16x32_bf16 v[0:3], v[200:203], v[204:207], v[0:3]
	s_barrier
	s_waitcnt vmcnt(0)
	ds_write_b128 v60, v[100:103]
	ds_write_b128 v60, v[104:107] offset:8704
	ds_write_b128 v60, v[108:111] offset:17408
	ds_write_b128 v60, v[112:115] offset:26112
	ds_write_b128 v60, v[116:119] offset:34816
	ds_write_b128 v60, v[120:123] offset:43520
	ds_write_b128 v60, v[124:127] offset:52224
	ds_write_b128 v60, v[128:131] offset:60928
	ds_write_b128 v61, v[132:135]
	s_waitcnt lgkmcnt(0)
	s_barrier
	ds_read_b128 v[176:179], v62
	ds_read_b128 v[180:183], v63
	ds_read_b128 v[184:187], v62 offset:64
	ds_read_b128 v[188:191], v63 offset:64
	ds_read_b128 v[192:195], v62 offset:128
	ds_read_b128 v[196:199], v63 offset:128
	ds_read_b128 v[200:203], v62 offset:192
	ds_read_b128 v[204:207], v63 offset:192
	s_waitcnt lgkmcnt(0)
	v_mfma_f32_16x16x32_bf16 v[0:3], v[176:179], v[180:183], v[0:3]
	v_mfma_f32_16x16x32_bf16 v[0:3], v[184:187], v[188:191], v[0:3]
	v_mfma_f32_16x16x32_bf16 v[0:3], v[192:195], v[196:199], v[0:3]
	v_mfma_f32_16x16x32_bf16 v[0:3], v[200:203], v[204:207], v[0:3]
	ds_read_b128 v[176:179], v62 offset:256
	ds_read_b128 v[180:183], v63 offset:256
	ds_read_b128 v[184:187], v62 offset:320
	ds_read_b128 v[188:191], v63 offset:320
	ds_read_b128 v[192:195], v62 offset:384
	ds_read_b128 v[196:199], v63 offset:384
	ds_read_b128 v[200:203], v62 offset:448
	ds_read_b128 v[204:207], v63 offset:448
	s_waitcnt lgkmcnt(0)
	v_mfma_f32_16x16x32_bf16 v[0:3], v[176:179], v[180:183], v[0:3]
	v_mfma_f32_16x16x32_bf16 v[0:3], v[184:187], v[188:191], v[0:3]
	v_mfma_f32_16x16x32_bf16 v[0:3], v[192:195], v[196:199], v[0:3]
	v_mfma_f32_16x16x32_bf16 v[0:3], v[200:203], v[204:207], v[0:3]
	s_barrier
	s_and_b32 s8, s16, 0xffffff80
	s_ashr_i32 s9, s8, 31
	v_lshl_add_u64 v[22:23], s[8:9], 2, v[18:19]
	global_load_dwordx4 v[22:25], v[22:23], off
	s_and_b64 vcc, exec, s[6:7]
	s_waitcnt vmcnt(0) lgkmcnt(0)
	s_nop 0
	v_pk_add_f32 v[0:1], v[0:1], v[22:23]
	v_pk_add_f32 v[2:3], v[2:3], v[24:25]
	v_mul_f32_e32 v22, 0x3d372713, v0
	v_mul_f32_e32 v23, 0x3d372713, v1
	v_mul_f32_e32 v24, 0x3d372713, v2
	v_mul_f32_e32 v25, 0x3d372713, v3
	v_mul_f32_e32 v22, v0, v22
	v_mul_f32_e32 v23, v1, v23
	v_mul_f32_e32 v24, v2, v24
	v_mul_f32_e32 v25, v3, v25
	v_fma_f32 v22, v0, v22, v0
	v_fma_f32 v23, v1, v23, v1
	v_fma_f32 v24, v2, v24, v2
	v_fma_f32 v25, v3, v25, v3
	v_mul_f32_e32 v22, 0x3f4c422a, v22
	v_mul_f32_e32 v23, 0x3f4c422a, v23
	v_mul_f32_e32 v24, 0x3f4c422a, v24
	v_mul_f32_e32 v25, 0x3f4c422a, v25
	v_add_f32_e32 v22, v22, v22
	v_add_f32_e32 v23, v23, v23
	v_add_f32_e32 v24, v24, v24
	v_add_f32_e32 v25, v25, v25
	v_mul_f32_e32 v22, 0x3fb8aa3b, v22
	v_mul_f32_e32 v23, 0x3fb8aa3b, v23
	v_mul_f32_e32 v24, 0x3fb8aa3b, v24
	v_mul_f32_e32 v25, 0x3fb8aa3b, v25
	v_exp_f32_e32 v22, v22
	v_exp_f32_e32 v23, v23
	v_exp_f32_e32 v24, v24
	v_exp_f32_e32 v25, v25
	v_add_f32_e32 v22, 1.0, v22
	v_add_f32_e32 v23, 1.0, v23
	v_add_f32_e32 v24, 1.0, v24
	v_add_f32_e32 v25, 1.0, v25
	v_rcp_f32_e32 v22, v22
	v_rcp_f32_e32 v23, v23
	v_rcp_f32_e32 v24, v24
	v_rcp_f32_e32 v25, v25
	v_pk_mul_f32 v[0:1], v[0:1], 0.5 op_sel_hi:[1,0]
	v_pk_fma_f32 v[22:23], v[22:23], 2.0, 1.0 op_sel_hi:[1,0,0] neg_lo:[1,0,0] neg_hi:[1,0,0]
	v_pk_mul_f32 v[2:3], v[2:3], 0.5 op_sel_hi:[1,0]
	v_pk_fma_f32 v[24:25], v[24:25], 2.0, 1.0 op_sel_hi:[1,0,0] neg_lo:[1,0,0] neg_hi:[1,0,0]
	v_pk_add_f32 v[22:23], v[22:23], 1.0 op_sel_hi:[1,0]
	v_pk_add_f32 v[24:25], v[24:25], 1.0 op_sel_hi:[1,0]
	v_pk_mul_f32 v[0:1], v[0:1], v[22:23]
	v_pk_mul_f32 v[2:3], v[2:3], v[24:25]
	v_cvt_pk_bf16_f32 v0, v0, v1
	v_cvt_pk_bf16_f32 v1, v2, v3
	ds_write_b64 v30, v[0:1]
	s_waitcnt lgkmcnt(0)
	s_barrier
	s_cbranch_vccz .LBB0_357
	s_lshl_b64 s[2:3], s[2:3], 14
	v_lshl_add_u64 v[26:27], v[8:9], 0, s[2:3]
	global_load_dwordx2 v[0:1], v[26:27], off
	global_load_dwordx2 v[2:3], v[26:27], off offset:32
	global_load_dwordx2 v[22:23], v[26:27], off offset:64
	global_load_dwordx2 v[24:25], v[26:27], off offset:96
	global_load_dwordx2 v[34:35], v[26:27], off offset:128
	global_load_dwordx2 v[36:37], v[26:27], off offset:160
	global_load_dwordx2 v[38:39], v[26:27], off offset:192
	global_load_dwordx2 v[40:41], v[26:27], off offset:224
	ds_read2_b64 v[42:45], v29 offset1:4
	s_and_b32 s9, s16, 15
	s_lshl_b32 s8, s17, 15
	s_mov_b64 s[2:3], -1
	s_cmpk_gt_u32 s16, 0x7f
	s_waitcnt vmcnt(0) lgkmcnt(0)
	v_mfma_f32_16x16x32_bf16 v[0:3], v[0:3], v[42:45], 0
	ds_read2_b64 v[42:45], v29 offset0:8 offset1:12
	s_waitcnt lgkmcnt(0)
	v_mfma_f32_16x16x32_bf16 v[0:3], v[22:25], v[42:45], v[0:3]
	ds_read2_b64 v[22:25], v29 offset0:16 offset1:20
	ds_read2_b64 v[42:45], v29 offset0:24 offset1:28
	s_waitcnt lgkmcnt(1)
	v_mfma_f32_16x16x32_bf16 v[0:3], v[34:37], v[22:25], v[0:3]
	s_waitcnt lgkmcnt(0)
	v_mfma_f32_16x16x32_bf16 v[22:25], v[38:41], v[42:45], v[0:3]
	s_nop 5
	v_lshl_or_b32 v2, s9, 4, v28
	s_nop 0
	v_cvt_pk_bf16_f32 v0, v22, v23
	v_cvt_pk_bf16_f32 v1, v24, v25
	s_cbranch_scc0 .LBB0_363
	s_add_u32 s2, s12, s8
	s_addc_u32 s3, s13, 0
	s_lshl_b32 s9, s9, 2
	s_and_b32 s9, s9, 4
	v_and_b32_e32 v3, 0xe3, v2
	v_or3_b32 v3, s9, v31, v3
	v_lshlrev_b32_e32 v136, 1, v3
	v_lshl_add_u64 v[22:23], s[2:3], 0, v[136:137]
	v_lshl_add_u64 v[24:25], v[22:23], 0, v[10:11]
	global_store_short v[24:25], v0, off
	v_lshl_add_u64 v[24:25], v[22:23], 0, v[12:13]
	global_store_short_d16_hi v[24:25], v0, off
	v_lshl_add_u64 v[24:25], v[22:23], 0, v[14:15]
	v_lshl_add_u64 v[22:23], v[22:23], 0, v[16:17]
	global_store_short v[24:25], v1, off
	global_store_short_d16_hi v[22:23], v1, off
	s_mov_b64 s[2:3], 0
